# SGU mixer: one dword touch per 128-byte line of the next unit's V rows and row statistics at the top of the current unit (L2 warm-up ahead of the real prefetch)
# baseline (speedup 1.0000x reference)
.LBB0_129:
	s_and_b32 s11, s10, 0xffffff80
	s_and_b32 s16, s6, 0x780
	v_add_u32_e32 v4, s11, v172
	v_add_u32_e32 v6, s11, v173
	s_lshl_b32 s84, s16, 1
	v_ashrrev_i32_e32 v5, 31, v4
	v_ashrrev_i32_e32 v7, 31, v6
	v_lshl_add_u64 v[2:3], v[150:151], 0, s[84:85]
	v_lshlrev_b64 v[162:163], 12, v[4:5]
	v_lshlrev_b64 v[160:161], 12, v[6:7]
	v_lshl_add_u64 v[4:5], v[2:3], 0, v[162:163]
	v_lshl_add_u64 v[6:7], v[2:3], 0, v[160:161]
	global_load_dwordx4 v[126:129], v[4:5], off
	global_load_dwordx4 v[122:125], v[6:7], off
	v_add_u32_e32 v4, s11, v174
	v_add_u32_e32 v6, s11, v175
	v_ashrrev_i32_e32 v5, 31, v4
	v_ashrrev_i32_e32 v7, 31, v6
	v_lshlrev_b64 v[158:159], 12, v[4:5]
	v_lshlrev_b64 v[156:157], 12, v[6:7]
	v_lshl_add_u64 v[4:5], v[2:3], 0, v[158:159]
	v_lshl_add_u64 v[2:3], v[2:3], 0, v[156:157]
	global_load_dwordx4 v[118:121], v[4:5], off
	global_load_dwordx4 v[114:117], v[2:3], off
	v_add_u32_e32 v2, s16, v168
	v_ashrrev_i32_e32 v3, 31, v2
	v_lshl_add_u64 v[2:3], v[2:3], 2, s[38:39]
	global_load_dword v184, v[2:3], off
	global_load_dword v0, v[2:3], off offset:128
	v_or_b32_e32 v2, s16, v169
	v_lshlrev_b32_e32 v2, 2, v2
	global_load_dwordx4 v[142:145], v2, s[44:45]
	global_load_dwordx4 v[138:141], v2, s[44:45] offset:32
	global_load_dwordx4 v[134:137], v2, s[44:45] offset:64
	global_load_dwordx4 v[130:133], v2, s[44:45] offset:96
	s_add_i32 s100, s10, s62
	s_and_b32 s100, s100, 0xffffff80
	s_add_i32 s101, s6, s22
	s_and_b32 s101, s101, 0x780
	s_lshl_b32 s101, s101, 1
	v_readfirstlane_b32 s26, v164
	s_nop 3
	s_cmpk_lt_u32 s26, 0x100
	s_cbranch_scc0 .Lsgu_pf_vss
	v_and_b32_e32 v4, 0xff, v164
	v_lshrrev_b32_e32 v5, 1, v4
	v_add_u32_e32 v5, s100, v5
	v_and_b32_e32 v4, 1, v4
	v_lshlrev_b32_e32 v4, 7, v4
	v_lshl_add_u32 v4, v5, 12, v4
	v_add_u32_e32 v4, s101, v4
	v_readlane_b32 s26, v252, 31
	v_readlane_b32 s27, v252, 32
	s_nop 4
	global_load_dword v250, v4, s[26:27]
	s_branch .Lsgu_pf_done
.Lsgu_pf_vss:
	v_and_b32_e32 v4, 0x7f, v164
	v_add_u32_e32 v4, s100, v4
	v_lshlrev_b32_e32 v4, 7, v4
	v_readlane_b32 s26, v252, 15
	v_readlane_b32 s27, v252, 16
	s_nop 4
	global_load_dword v250, v4, s[26:27]
.Lsgu_pf_done:
	s_and_saveexec_b64 s[26:27], s[40:41]
	s_cbranch_execz .LBB0_131
	s_waitcnt vmcnt(26)
	v_mov_b32_e32 v2, v46
	v_mov_b32_e32 v3, v42
	v_mov_b32_e32 v4, v47
	v_mov_b32_e32 v5, v43
	v_pk_add_f32 v[2:3], v[2:3], v[4:5]
	v_mov_b32_e32 v4, v48
	v_mov_b32_e32 v5, v44
	v_mov_b32_e32 v6, v49
	v_mov_b32_e32 v7, v45
	v_pk_add_f32 v[4:5], v[4:5], v[6:7]
	v_mov_b32_e32 v6, v38
	v_pk_add_f32 v[2:3], v[2:3], v[4:5]
	v_mov_b32_e32 v4, v39
	v_mov_b32_e32 v5, v40
	v_mov_b32_e32 v7, v41
	v_pk_add_f32 v[4:5], v[4:5], v[6:7]
	v_add_f32_e32 v2, 0, v2
	v_pk_add_f32 v[4:5], v[4:5], v[4:5] op_sel:[0,1] op_sel_hi:[1,0]
	v_add_f32_e32 v2, v2, v3
	v_add_f32_e32 v6, v34, v35
	v_add_f32_e32 v8, v36, v37
	s_waitcnt vmcnt(22)
	v_mov_b32_e32 v3, v62
	v_mov_b32_e32 v5, v63
	v_mov_b32_e32 v7, v64
	v_mov_b32_e32 v9, v65
	v_pk_add_f32 v[2:3], v[2:3], v[4:5]
	v_pk_add_f32 v[4:5], v[6:7], v[8:9]
	v_mov_b32_e32 v6, v58
	v_pk_add_f32 v[2:3], v[2:3], v[4:5]
	v_mov_b32_e32 v4, v59
	v_mov_b32_e32 v5, v60
	v_mov_b32_e32 v7, v61
	v_pk_add_f32 v[4:5], v[4:5], v[6:7]
	v_pk_add_f32 v[2:3], v[2:3], v[2:3] op_sel:[0,1] op_sel_hi:[1,0]
	v_pk_add_f32 v[4:5], v[4:5], v[4:5] op_sel:[0,1] op_sel_hi:[1,0]
	v_add_f32_e32 v6, v54, v55
	v_add_f32_e32 v8, v56, v57
	v_mov_b32_e32 v3, v50
	v_mov_b32_e32 v5, v51
	v_mov_b32_e32 v7, v52
	v_mov_b32_e32 v9, v53
	v_pk_add_f32 v[2:3], v[2:3], v[4:5]
	v_pk_add_f32 v[4:5], v[6:7], v[8:9]
	s_nop 0
	v_pk_add_f32 v[2:3], v[2:3], v[4:5]
	s_nop 0
	v_add_f32_e32 v2, v2, v3
	v_fmamk_f32 v2, v2, 0x3a000000, v218
	v_mul_f32_e32 v3, 0x4f800000, v2
	v_cmp_gt_f32_e32 vcc, s55, v2
	s_nop 1
	v_cndmask_b32_e32 v2, v2, v3, vcc
	v_sqrt_f32_e32 v3, v2
	s_nop 0
	v_add_u32_e32 v4, -1, v3
	v_fma_f32 v5, -v4, v3, v2
	v_cmp_ge_f32_e64 s[42:43], 0, v5
	v_add_u32_e32 v5, 1, v3
	s_nop 0
	v_cndmask_b32_e64 v4, v3, v4, s[42:43]
	v_fma_f32 v3, -v5, v3, v2
	v_cmp_lt_f32_e64 s[42:43], 0, v3
	s_nop 1
	v_cndmask_b32_e64 v3, v4, v5, s[42:43]
	v_mul_f32_e32 v4, 0x37800000, v3
	v_cndmask_b32_e32 v3, v3, v4, vcc
	v_cmp_class_f32_e32 vcc, v2, v219
	s_nop 1
	v_cndmask_b32_e32 v2, v3, v2, vcc
	v_div_scale_f32 v3, s[16:17], v2, v2, 1.0
	v_rcp_f32_e32 v4, v3
	s_nop 0
	v_fma_f32 v5, -v3, v4, 1.0
	v_fmac_f32_e32 v4, v5, v4
	v_div_scale_f32 v5, vcc, 1.0, v2, 1.0
	v_mul_f32_e32 v6, v5, v4
	v_fma_f32 v7, -v3, v6, v5
	v_fmac_f32_e32 v6, v7, v4
	v_fma_f32 v3, -v3, v6, v5
	v_div_fmas_f32 v3, v3, v4, v6
	v_div_fixup_f32 v2, v3, v2, 1.0
	ds_write_b32 v170, v2
